# P2 and P11 loops: issue the LDS-DMA loads before the ds_reads in each phase (longer latency lead)
# baseline (speedup 1.0000x reference)
.LBB0_325:
	s_add_u32 s50, s46, 0x10000
	s_addc_u32 s51, s47, 0
	s_cmp_eq_u32 s91, 40
	s_cselect_b32 s55, s5, s51
	s_cselect_b32 s54, s4, s50
	s_cselect_b32 s53, s43, s90
	s_cselect_b32 s52, s42, s89
	v_lshl_add_u64 v[144:145], s[46:47], 0, v[136:137]
	s_add_i32 m0, s35, 0xc000
	s_nop 0
	global_load_lds_dwordx4 v[144:145], off
	v_lshl_add_u64 v[144:145], s[46:47], 0, v[138:139]
	s_add_i32 m0, s35, 0xe000
	s_nop 0
	global_load_lds_dwordx4 v[144:145], off
	ds_read_b128 v[152:155], v149
	ds_read_b128 v[156:159], v149 offset:1024
	ds_read_b128 v[160:163], v149 offset:2048
	ds_read_b128 v[164:167], v149 offset:3072
	ds_read_b128 v[168:171], v150
	ds_read_b128 v[172:175], v150 offset:1024
	ds_read_b128 v[176:179], v150 offset:2048
	ds_read_b128 v[180:183], v150 offset:3072
	ds_read_b128 v[184:187], v151
	ds_read_b128 v[190:193], v151 offset:1024
	ds_read_b128 v[194:197], v151 offset:2048
	ds_read_b128 v[198:201], v151 offset:3072
	ds_read_b128 v[202:205], v151 offset:4096
	ds_read_b128 v[206:209], v151 offset:5120
	ds_read_b128 v[210:213], v151 offset:6144
	ds_read_b128 v[214:217], v151 offset:7168
	s_waitcnt vmcnt(8)
	s_waitcnt lgkmcnt(0)
	s_nop 0
	s_barrier
	s_waitcnt lgkmcnt(0)
	v_mfma_f32_16x16x32_bf16 v[124:127], v[152:155], v[184:187], v[124:127]
	v_mfma_f32_16x16x32_bf16 v[120:123], v[160:163], v[184:187], v[120:123]
	v_mfma_f32_16x16x32_bf16 v[116:119], v[152:155], v[194:197], v[116:119]
	v_mfma_f32_16x16x32_bf16 v[108:111], v[160:163], v[194:197], v[108:111]
	v_mfma_f32_16x16x32_bf16 v[100:103], v[152:155], v[202:205], v[100:103]
	v_mfma_f32_16x16x32_bf16 v[92:95], v[160:163], v[202:205], v[92:95]
	v_mfma_f32_16x16x32_bf16 v[84:87], v[152:155], v[210:213], v[84:87]
	v_mfma_f32_16x16x32_bf16 v[76:79], v[160:163], v[210:213], v[76:79]
	v_mfma_f32_16x16x32_bf16 v[124:127], v[156:159], v[190:193], v[124:127]
	v_mfma_f32_16x16x32_bf16 v[120:123], v[164:167], v[190:193], v[120:123]
	v_mfma_f32_16x16x32_bf16 v[116:119], v[156:159], v[198:201], v[116:119]
	v_mfma_f32_16x16x32_bf16 v[108:111], v[164:167], v[198:201], v[108:111]
	v_mfma_f32_16x16x32_bf16 v[100:103], v[156:159], v[206:209], v[100:103]
	v_mfma_f32_16x16x32_bf16 v[92:95], v[164:167], v[206:209], v[92:95]
	v_mfma_f32_16x16x32_bf16 v[84:87], v[156:159], v[214:217], v[84:87]
	v_mfma_f32_16x16x32_bf16 v[76:79], v[164:167], v[214:217], v[76:79]
	v_mfma_f32_16x16x32_bf16 v[112:115], v[168:171], v[184:187], v[112:115]
	v_mfma_f32_16x16x32_bf16 v[104:107], v[176:179], v[184:187], v[104:107]
	v_mfma_f32_16x16x32_bf16 v[96:99], v[168:171], v[194:197], v[96:99]
	v_mfma_f32_16x16x32_bf16 v[88:91], v[176:179], v[194:197], v[88:91]
	v_mfma_f32_16x16x32_bf16 v[80:83], v[168:171], v[202:205], v[80:83]
	v_mfma_f32_16x16x32_bf16 v[72:75], v[176:179], v[202:205], v[72:75]
	v_mfma_f32_16x16x32_bf16 v[68:71], v[168:171], v[210:213], v[68:71]
	v_mfma_f32_16x16x32_bf16 v[64:67], v[176:179], v[210:213], v[64:67]
	v_mfma_f32_16x16x32_bf16 v[112:115], v[172:175], v[190:193], v[112:115]
	v_mfma_f32_16x16x32_bf16 v[104:107], v[180:183], v[190:193], v[104:107]
	v_mfma_f32_16x16x32_bf16 v[96:99], v[172:175], v[198:201], v[96:99]
	v_mfma_f32_16x16x32_bf16 v[88:91], v[180:183], v[198:201], v[88:91]
	v_mfma_f32_16x16x32_bf16 v[80:83], v[172:175], v[206:209], v[80:83]
	v_mfma_f32_16x16x32_bf16 v[72:75], v[180:183], v[206:209], v[72:75]
	v_mfma_f32_16x16x32_bf16 v[68:71], v[172:175], v[214:217], v[68:71]
	v_mfma_f32_16x16x32_bf16 v[64:67], v[180:183], v[214:217], v[64:67]
	s_barrier
	s_add_i32 s28, s76, s34
	v_lshl_add_u64 v[144:145], s[52:53], 0, v[130:131]
	s_mov_b32 m0, s28
	s_nop 0
	global_load_lds_dwordx4 v[144:145], off
	s_add_i32 m0, s28, 0x2000
	s_add_u32 s28, s52, 0xb0000
	v_lshl_add_u64 v[218:219], s[52:53], 0, v[134:135]
	s_addc_u32 s29, s53, 0
	s_add_i32 s33, s77, s34
	global_load_lds_dwordx4 v[218:219], off
	v_lshl_add_u64 v[220:221], s[28:29], 0, v[130:131]
	s_mov_b32 m0, s33
	v_lshl_add_u64 v[222:223], s[54:55], 0, v[132:133]
	global_load_lds_dwordx4 v[220:221], off
	v_lshl_add_u64 v[220:221], s[28:29], 0, v[134:135]
	s_add_i32 m0, s33, 0x2000
	s_nop 0
	global_load_lds_dwordx4 v[220:221], off
	v_lshl_add_u64 v[220:221], s[54:55], 0, v[128:129]
	s_mov_b32 m0, s35
	s_nop 0
	global_load_lds_dwordx4 v[220:221], off
	s_mov_b32 m0, s60
	s_nop 0
	global_load_lds_dwordx4 v[222:223], off
	ds_read_b128 v[184:187], v151 offset:16384
	ds_read_b128 v[190:193], v151 offset:17408
	ds_read_b128 v[194:197], v151 offset:18432
	ds_read_b128 v[198:201], v151 offset:19456
	ds_read_b128 v[202:205], v151 offset:20480
	ds_read_b128 v[206:209], v151 offset:21504
	ds_read_b128 v[210:213], v151 offset:22528
	ds_read_b128 v[214:217], v151 offset:23552
	s_waitcnt vmcnt(8)
	s_waitcnt lgkmcnt(0)
	s_barrier
	s_waitcnt lgkmcnt(0)
	v_mfma_f32_16x16x32_bf16 v[60:63], v[152:155], v[184:187], v[60:63]
	v_mfma_f32_16x16x32_bf16 v[56:59], v[160:163], v[184:187], v[56:59]
	v_mfma_f32_16x16x32_bf16 v[52:55], v[152:155], v[194:197], v[52:55]
	v_mfma_f32_16x16x32_bf16 v[44:47], v[160:163], v[194:197], v[44:47]
	v_mfma_f32_16x16x32_bf16 v[36:39], v[152:155], v[202:205], v[36:39]
	v_mfma_f32_16x16x32_bf16 v[28:31], v[160:163], v[202:205], v[28:31]
	v_mfma_f32_16x16x32_bf16 v[20:23], v[152:155], v[210:213], v[20:23]
	v_mfma_f32_16x16x32_bf16 v[12:15], v[160:163], v[210:213], v[12:15]
	v_mfma_f32_16x16x32_bf16 v[60:63], v[156:159], v[190:193], v[60:63]
	v_mfma_f32_16x16x32_bf16 v[56:59], v[164:167], v[190:193], v[56:59]
	v_mfma_f32_16x16x32_bf16 v[52:55], v[156:159], v[198:201], v[52:55]
	v_mfma_f32_16x16x32_bf16 v[44:47], v[164:167], v[198:201], v[44:47]
	v_mfma_f32_16x16x32_bf16 v[36:39], v[156:159], v[206:209], v[36:39]
	v_mfma_f32_16x16x32_bf16 v[28:31], v[164:167], v[206:209], v[28:31]
	v_mfma_f32_16x16x32_bf16 v[20:23], v[156:159], v[214:217], v[20:23]
	v_mfma_f32_16x16x32_bf16 v[12:15], v[164:167], v[214:217], v[12:15]
	v_mfma_f32_16x16x32_bf16 v[48:51], v[168:171], v[184:187], v[48:51]
	v_mfma_f32_16x16x32_bf16 v[40:43], v[176:179], v[184:187], v[40:43]
	v_mfma_f32_16x16x32_bf16 v[32:35], v[168:171], v[194:197], v[32:35]
	v_mfma_f32_16x16x32_bf16 v[24:27], v[176:179], v[194:197], v[24:27]
	v_mfma_f32_16x16x32_bf16 v[16:19], v[168:171], v[202:205], v[16:19]
	v_mfma_f32_16x16x32_bf16 v[8:11], v[176:179], v[202:205], v[8:11]
	v_mfma_f32_16x16x32_bf16 v[4:7], v[168:171], v[210:213], v[4:7]
	v_mfma_f32_16x16x32_bf16 v[0:3], v[176:179], v[210:213], v[0:3]
	v_mfma_f32_16x16x32_bf16 v[48:51], v[172:175], v[190:193], v[48:51]
	v_mfma_f32_16x16x32_bf16 v[40:43], v[180:183], v[190:193], v[40:43]
	v_mfma_f32_16x16x32_bf16 v[32:35], v[172:175], v[198:201], v[32:35]
	v_mfma_f32_16x16x32_bf16 v[24:27], v[180:183], v[198:201], v[24:27]
	v_mfma_f32_16x16x32_bf16 v[16:19], v[172:175], v[206:209], v[16:19]
	v_mfma_f32_16x16x32_bf16 v[8:11], v[180:183], v[206:209], v[8:11]
	v_mfma_f32_16x16x32_bf16 v[4:7], v[172:175], v[214:217], v[4:7]
	v_mfma_f32_16x16x32_bf16 v[0:3], v[180:183], v[214:217], v[0:3]
	s_barrier
	s_add_i32 s33, 0, 0x18000
	s_add_i32 s46, 0, 0x1c000
	v_add_u32_e32 v164, s33, v147
	v_add_u32_e32 v180, s46, v147
	s_add_u32 s28, s54, 0x4000
	s_addc_u32 s29, s55, 0
	s_mov_b32 m0, s61
	v_lshl_add_u64 v[224:225], s[28:29], 0, v[128:129]
	global_load_lds_dwordx4 v[224:225], off
	v_lshl_add_u64 v[224:225], s[28:29], 0, v[132:133]
	s_mov_b32 m0, s62
	s_nop 0
	global_load_lds_dwordx4 v[224:225], off
	ds_read_b128 v[152:155], v164
	ds_read_b128 v[156:159], v164 offset:1024
	ds_read_b128 v[160:163], v164 offset:2048
	ds_read_b128 v[164:167], v164 offset:3072
	ds_read_b128 v[168:171], v180
	ds_read_b128 v[172:175], v180 offset:1024
	ds_read_b128 v[176:179], v180 offset:2048
	ds_read_b128 v[180:183], v180 offset:3072
	ds_read_b128 v[184:187], v151 offset:32768
	ds_read_b128 v[190:193], v151 offset:33792
	ds_read_b128 v[194:197], v151 offset:34816
	ds_read_b128 v[198:201], v151 offset:35840
	ds_read_b128 v[202:205], v151 offset:36864
	ds_read_b128 v[206:209], v151 offset:37888
	ds_read_b128 v[210:213], v151 offset:38912
	ds_read_b128 v[214:217], v151 offset:39936
	s_waitcnt vmcnt(8)
	s_waitcnt lgkmcnt(0)
	s_nop 0
	s_barrier
	s_waitcnt lgkmcnt(0)
	v_mfma_f32_16x16x32_bf16 v[124:127], v[152:155], v[184:187], v[124:127]
	v_mfma_f32_16x16x32_bf16 v[120:123], v[160:163], v[184:187], v[120:123]
	v_mfma_f32_16x16x32_bf16 v[116:119], v[152:155], v[194:197], v[116:119]
	v_mfma_f32_16x16x32_bf16 v[108:111], v[160:163], v[194:197], v[108:111]
	v_mfma_f32_16x16x32_bf16 v[100:103], v[152:155], v[202:205], v[100:103]
	v_mfma_f32_16x16x32_bf16 v[92:95], v[160:163], v[202:205], v[92:95]
	v_mfma_f32_16x16x32_bf16 v[84:87], v[152:155], v[210:213], v[84:87]
	v_mfma_f32_16x16x32_bf16 v[76:79], v[160:163], v[210:213], v[76:79]
	v_mfma_f32_16x16x32_bf16 v[124:127], v[156:159], v[190:193], v[124:127]
	v_mfma_f32_16x16x32_bf16 v[120:123], v[164:167], v[190:193], v[120:123]
	v_mfma_f32_16x16x32_bf16 v[116:119], v[156:159], v[198:201], v[116:119]
	v_mfma_f32_16x16x32_bf16 v[108:111], v[164:167], v[198:201], v[108:111]
	v_mfma_f32_16x16x32_bf16 v[100:103], v[156:159], v[206:209], v[100:103]
	v_mfma_f32_16x16x32_bf16 v[92:95], v[164:167], v[206:209], v[92:95]
	v_mfma_f32_16x16x32_bf16 v[84:87], v[156:159], v[214:217], v[84:87]
	v_mfma_f32_16x16x32_bf16 v[76:79], v[164:167], v[214:217], v[76:79]
	v_mfma_f32_16x16x32_bf16 v[112:115], v[168:171], v[184:187], v[112:115]
	v_mfma_f32_16x16x32_bf16 v[104:107], v[176:179], v[184:187], v[104:107]
	v_mfma_f32_16x16x32_bf16 v[96:99], v[168:171], v[194:197], v[96:99]
	v_mfma_f32_16x16x32_bf16 v[88:91], v[176:179], v[194:197], v[88:91]
	v_mfma_f32_16x16x32_bf16 v[80:83], v[168:171], v[202:205], v[80:83]
	v_mfma_f32_16x16x32_bf16 v[72:75], v[176:179], v[202:205], v[72:75]
	v_mfma_f32_16x16x32_bf16 v[68:71], v[168:171], v[210:213], v[68:71]
	v_mfma_f32_16x16x32_bf16 v[64:67], v[176:179], v[210:213], v[64:67]
	v_mfma_f32_16x16x32_bf16 v[112:115], v[172:175], v[190:193], v[112:115]
	v_mfma_f32_16x16x32_bf16 v[104:107], v[180:183], v[190:193], v[104:107]
	v_mfma_f32_16x16x32_bf16 v[96:99], v[172:175], v[198:201], v[96:99]
	v_mfma_f32_16x16x32_bf16 v[88:91], v[180:183], v[198:201], v[88:91]
	v_mfma_f32_16x16x32_bf16 v[80:83], v[172:175], v[206:209], v[80:83]
	v_mfma_f32_16x16x32_bf16 v[72:75], v[180:183], v[206:209], v[72:75]
	v_mfma_f32_16x16x32_bf16 v[68:71], v[172:175], v[214:217], v[68:71]
	v_mfma_f32_16x16x32_bf16 v[64:67], v[180:183], v[214:217], v[64:67]
	s_barrier
	s_add_i32 s28, s33, s34
	v_lshl_add_u64 v[144:145], v[144:145], 0, s[8:9]
	s_mov_b32 m0, s28
	s_nop 0
	global_load_lds_dwordx4 v[144:145], off
	s_add_i32 m0, s28, 0x2000
	s_add_u32 s28, s52, 0xb0080
	v_lshl_add_u64 v[144:145], v[218:219], 0, s[8:9]
	s_addc_u32 s29, s53, 0
	s_add_i32 s33, s46, s34
	global_load_lds_dwordx4 v[144:145], off
	v_lshl_add_u64 v[144:145], s[28:29], 0, v[130:131]
	s_mov_b32 m0, s33
	s_nop 0
	global_load_lds_dwordx4 v[144:145], off
	v_lshl_add_u64 v[144:145], s[28:29], 0, v[134:135]
	s_add_i32 m0, s33, 0x2000
	s_nop 0
	global_load_lds_dwordx4 v[144:145], off
	v_lshl_add_u64 v[144:145], v[220:221], 0, s[92:93]
	s_mov_b32 m0, s64
	s_nop 0
	global_load_lds_dwordx4 v[144:145], off
	v_lshl_add_u64 v[144:145], v[222:223], 0, s[92:93]
	s_mov_b32 m0, s65
	s_nop 0
	global_load_lds_dwordx4 v[144:145], off
	ds_read_b128 v[184:187], v151 offset:49152
	ds_read_b128 v[190:193], v151 offset:50176
	ds_read_b128 v[194:197], v151 offset:51200
	ds_read_b128 v[198:201], v151 offset:52224
	ds_read_b128 v[202:205], v151 offset:53248
	ds_read_b128 v[206:209], v151 offset:54272
	ds_read_b128 v[210:213], v151 offset:55296
	ds_read_b128 v[214:217], v151 offset:56320
	s_waitcnt vmcnt(8)
	s_waitcnt lgkmcnt(0)
	s_nop 0
	s_barrier
	s_waitcnt lgkmcnt(0)
	v_mfma_f32_16x16x32_bf16 v[60:63], v[152:155], v[184:187], v[60:63]
	v_mfma_f32_16x16x32_bf16 v[56:59], v[160:163], v[184:187], v[56:59]
	v_mfma_f32_16x16x32_bf16 v[52:55], v[152:155], v[194:197], v[52:55]
	v_mfma_f32_16x16x32_bf16 v[44:47], v[160:163], v[194:197], v[44:47]
	v_mfma_f32_16x16x32_bf16 v[36:39], v[152:155], v[202:205], v[36:39]
	v_mfma_f32_16x16x32_bf16 v[28:31], v[160:163], v[202:205], v[28:31]
	v_mfma_f32_16x16x32_bf16 v[20:23], v[152:155], v[210:213], v[20:23]
	v_mfma_f32_16x16x32_bf16 v[12:15], v[160:163], v[210:213], v[12:15]
	v_mfma_f32_16x16x32_bf16 v[60:63], v[156:159], v[190:193], v[60:63]
	v_mfma_f32_16x16x32_bf16 v[56:59], v[164:167], v[190:193], v[56:59]
	v_mfma_f32_16x16x32_bf16 v[52:55], v[156:159], v[198:201], v[52:55]
	v_mfma_f32_16x16x32_bf16 v[44:47], v[164:167], v[198:201], v[44:47]
	v_mfma_f32_16x16x32_bf16 v[36:39], v[156:159], v[206:209], v[36:39]
	v_mfma_f32_16x16x32_bf16 v[28:31], v[164:167], v[206:209], v[28:31]
	v_mfma_f32_16x16x32_bf16 v[20:23], v[156:159], v[214:217], v[20:23]
	v_mfma_f32_16x16x32_bf16 v[12:15], v[164:167], v[214:217], v[12:15]
	v_mfma_f32_16x16x32_bf16 v[48:51], v[168:171], v[184:187], v[48:51]
	v_mfma_f32_16x16x32_bf16 v[40:43], v[176:179], v[184:187], v[40:43]
	v_mfma_f32_16x16x32_bf16 v[32:35], v[168:171], v[194:197], v[32:35]
	v_mfma_f32_16x16x32_bf16 v[24:27], v[176:179], v[194:197], v[24:27]
	v_mfma_f32_16x16x32_bf16 v[16:19], v[168:171], v[202:205], v[16:19]
	v_mfma_f32_16x16x32_bf16 v[8:11], v[176:179], v[202:205], v[8:11]
	v_mfma_f32_16x16x32_bf16 v[4:7], v[168:171], v[210:213], v[4:7]
	v_mfma_f32_16x16x32_bf16 v[0:3], v[176:179], v[210:213], v[0:3]
	v_mfma_f32_16x16x32_bf16 v[48:51], v[172:175], v[190:193], v[48:51]
	v_mfma_f32_16x16x32_bf16 v[40:43], v[180:183], v[190:193], v[40:43]
	v_mfma_f32_16x16x32_bf16 v[32:35], v[172:175], v[198:201], v[32:35]
	v_mfma_f32_16x16x32_bf16 v[24:27], v[180:183], v[198:201], v[24:27]
	v_mfma_f32_16x16x32_bf16 v[16:19], v[172:175], v[206:209], v[16:19]
	v_mfma_f32_16x16x32_bf16 v[8:11], v[180:183], v[206:209], v[8:11]
	v_mfma_f32_16x16x32_bf16 v[4:7], v[172:175], v[214:217], v[4:7]
	v_mfma_f32_16x16x32_bf16 v[0:3], v[180:183], v[214:217], v[0:3]
	s_barrier
	s_add_i32 s91, s91, 2
	s_add_u32 s89, s89, 0x100
	s_addc_u32 s90, s90, 0
	s_cmp_gt_u32 s91, 41
	s_mov_b64 s[46:47], s[50:51]
	s_cbranch_scc0 .LBB0_325
	s_and_b64 vcc, exec, s[10:11]
	s_cbranch_vccz .LBB0_328
	s_barrier

.LBB0_1388:
	s_add_u32 s36, s28, 0x10000
	s_addc_u32 s37, s29, 0
	s_cmp_eq_u32 s59, 40
	s_cselect_b32 s41, s5, s37
	s_cselect_b32 s40, s4, s36
	s_cselect_b32 s39, s27, s58
	s_cselect_b32 s38, s26, s57
	v_lshl_add_u64 v[144:145], s[28:29], 0, v[136:137]
	s_add_i32 m0, s34, 0xc000
	s_nop 0
	global_load_lds_dwordx4 v[144:145], off
	v_lshl_add_u64 v[144:145], s[28:29], 0, v[138:139]
	s_add_i32 m0, s34, 0xe000
	s_nop 0
	global_load_lds_dwordx4 v[144:145], off
	ds_read_b128 v[152:155], v149
	ds_read_b128 v[156:159], v149 offset:1024
	ds_read_b128 v[160:163], v149 offset:2048
	ds_read_b128 v[164:167], v149 offset:3072
	ds_read_b128 v[168:171], v150
	ds_read_b128 v[172:175], v150 offset:1024
	ds_read_b128 v[176:179], v150 offset:2048
	ds_read_b128 v[180:183], v150 offset:3072
	ds_read_b128 v[184:187], v151
	ds_read_b128 v[190:193], v151 offset:1024
	ds_read_b128 v[194:197], v151 offset:2048
	ds_read_b128 v[198:201], v151 offset:3072
	ds_read_b128 v[202:205], v151 offset:4096
	ds_read_b128 v[206:209], v151 offset:5120
	ds_read_b128 v[210:213], v151 offset:6144
	ds_read_b128 v[214:217], v151 offset:7168
	s_waitcnt vmcnt(8)
	s_waitcnt lgkmcnt(0)
	s_nop 0
	s_barrier
	s_waitcnt lgkmcnt(0)
	v_mfma_f32_16x16x32_bf16 v[124:127], v[152:155], v[184:187], v[124:127]
	v_mfma_f32_16x16x32_bf16 v[120:123], v[160:163], v[184:187], v[120:123]
	v_mfma_f32_16x16x32_bf16 v[116:119], v[152:155], v[194:197], v[116:119]
	v_mfma_f32_16x16x32_bf16 v[108:111], v[160:163], v[194:197], v[108:111]
	v_mfma_f32_16x16x32_bf16 v[100:103], v[152:155], v[202:205], v[100:103]
	v_mfma_f32_16x16x32_bf16 v[92:95], v[160:163], v[202:205], v[92:95]
	v_mfma_f32_16x16x32_bf16 v[84:87], v[152:155], v[210:213], v[84:87]
	v_mfma_f32_16x16x32_bf16 v[76:79], v[160:163], v[210:213], v[76:79]
	v_mfma_f32_16x16x32_bf16 v[124:127], v[156:159], v[190:193], v[124:127]
	v_mfma_f32_16x16x32_bf16 v[120:123], v[164:167], v[190:193], v[120:123]
	v_mfma_f32_16x16x32_bf16 v[116:119], v[156:159], v[198:201], v[116:119]
	v_mfma_f32_16x16x32_bf16 v[108:111], v[164:167], v[198:201], v[108:111]
	v_mfma_f32_16x16x32_bf16 v[100:103], v[156:159], v[206:209], v[100:103]
	v_mfma_f32_16x16x32_bf16 v[92:95], v[164:167], v[206:209], v[92:95]
	v_mfma_f32_16x16x32_bf16 v[84:87], v[156:159], v[214:217], v[84:87]
	v_mfma_f32_16x16x32_bf16 v[76:79], v[164:167], v[214:217], v[76:79]
	v_mfma_f32_16x16x32_bf16 v[112:115], v[168:171], v[184:187], v[112:115]
	v_mfma_f32_16x16x32_bf16 v[104:107], v[176:179], v[184:187], v[104:107]
	v_mfma_f32_16x16x32_bf16 v[96:99], v[168:171], v[194:197], v[96:99]
	v_mfma_f32_16x16x32_bf16 v[88:91], v[176:179], v[194:197], v[88:91]
	v_mfma_f32_16x16x32_bf16 v[80:83], v[168:171], v[202:205], v[80:83]
	v_mfma_f32_16x16x32_bf16 v[72:75], v[176:179], v[202:205], v[72:75]
	v_mfma_f32_16x16x32_bf16 v[68:71], v[168:171], v[210:213], v[68:71]
	v_mfma_f32_16x16x32_bf16 v[64:67], v[176:179], v[210:213], v[64:67]
	v_mfma_f32_16x16x32_bf16 v[112:115], v[172:175], v[190:193], v[112:115]
	v_mfma_f32_16x16x32_bf16 v[104:107], v[180:183], v[190:193], v[104:107]
	v_mfma_f32_16x16x32_bf16 v[96:99], v[172:175], v[198:201], v[96:99]
	v_mfma_f32_16x16x32_bf16 v[88:91], v[180:183], v[198:201], v[88:91]
	v_mfma_f32_16x16x32_bf16 v[80:83], v[172:175], v[206:209], v[80:83]
	v_mfma_f32_16x16x32_bf16 v[72:75], v[180:183], v[206:209], v[72:75]
	v_mfma_f32_16x16x32_bf16 v[68:71], v[172:175], v[214:217], v[68:71]
	v_mfma_f32_16x16x32_bf16 v[64:67], v[180:183], v[214:217], v[64:67]
	s_barrier
	s_add_i32 s28, s47, s13
	v_lshl_add_u64 v[144:145], s[38:39], 0, v[130:131]
	s_mov_b32 m0, s28
	s_nop 0
	global_load_lds_dwordx4 v[144:145], off
	s_add_i32 m0, s28, 0x2000
	s_add_u32 s28, s38, 0xb0000
	v_lshl_add_u64 v[218:219], s[38:39], 0, v[134:135]
	s_addc_u32 s29, s39, 0
	s_add_i32 s33, s48, s13
	global_load_lds_dwordx4 v[218:219], off
	v_lshl_add_u64 v[220:221], s[28:29], 0, v[130:131]
	s_mov_b32 m0, s33
	v_lshl_add_u64 v[222:223], s[40:41], 0, v[132:133]
	global_load_lds_dwordx4 v[220:221], off
	v_lshl_add_u64 v[220:221], s[28:29], 0, v[134:135]
	s_add_i32 m0, s33, 0x2000
	s_nop 0
	global_load_lds_dwordx4 v[220:221], off
	v_lshl_add_u64 v[220:221], s[40:41], 0, v[128:129]
	s_mov_b32 m0, s34
	s_nop 0
	global_load_lds_dwordx4 v[220:221], off
	s_mov_b32 m0, s35
	s_nop 0
	global_load_lds_dwordx4 v[222:223], off
	ds_read_b128 v[184:187], v151 offset:16384
	ds_read_b128 v[190:193], v151 offset:17408
	ds_read_b128 v[194:197], v151 offset:18432
	ds_read_b128 v[198:201], v151 offset:19456
	ds_read_b128 v[202:205], v151 offset:20480
	ds_read_b128 v[206:209], v151 offset:21504
	ds_read_b128 v[210:213], v151 offset:22528
	ds_read_b128 v[214:217], v151 offset:23552
	s_waitcnt vmcnt(8)
	s_waitcnt lgkmcnt(0)
	s_barrier
	s_waitcnt lgkmcnt(0)
	v_mfma_f32_16x16x32_bf16 v[60:63], v[152:155], v[184:187], v[60:63]
	v_mfma_f32_16x16x32_bf16 v[56:59], v[160:163], v[184:187], v[56:59]
	v_mfma_f32_16x16x32_bf16 v[52:55], v[152:155], v[194:197], v[52:55]
	v_mfma_f32_16x16x32_bf16 v[44:47], v[160:163], v[194:197], v[44:47]
	v_mfma_f32_16x16x32_bf16 v[36:39], v[152:155], v[202:205], v[36:39]
	v_mfma_f32_16x16x32_bf16 v[28:31], v[160:163], v[202:205], v[28:31]
	v_mfma_f32_16x16x32_bf16 v[20:23], v[152:155], v[210:213], v[20:23]
	v_mfma_f32_16x16x32_bf16 v[12:15], v[160:163], v[210:213], v[12:15]
	v_mfma_f32_16x16x32_bf16 v[60:63], v[156:159], v[190:193], v[60:63]
	v_mfma_f32_16x16x32_bf16 v[56:59], v[164:167], v[190:193], v[56:59]
	v_mfma_f32_16x16x32_bf16 v[52:55], v[156:159], v[198:201], v[52:55]
	v_mfma_f32_16x16x32_bf16 v[44:47], v[164:167], v[198:201], v[44:47]
	v_mfma_f32_16x16x32_bf16 v[36:39], v[156:159], v[206:209], v[36:39]
	v_mfma_f32_16x16x32_bf16 v[28:31], v[164:167], v[206:209], v[28:31]
	v_mfma_f32_16x16x32_bf16 v[20:23], v[156:159], v[214:217], v[20:23]
	v_mfma_f32_16x16x32_bf16 v[12:15], v[164:167], v[214:217], v[12:15]
	v_mfma_f32_16x16x32_bf16 v[48:51], v[168:171], v[184:187], v[48:51]
	v_mfma_f32_16x16x32_bf16 v[40:43], v[176:179], v[184:187], v[40:43]
	v_mfma_f32_16x16x32_bf16 v[32:35], v[168:171], v[194:197], v[32:35]
	v_mfma_f32_16x16x32_bf16 v[24:27], v[176:179], v[194:197], v[24:27]
	v_mfma_f32_16x16x32_bf16 v[16:19], v[168:171], v[202:205], v[16:19]
	v_mfma_f32_16x16x32_bf16 v[8:11], v[176:179], v[202:205], v[8:11]
	v_mfma_f32_16x16x32_bf16 v[4:7], v[168:171], v[210:213], v[4:7]
	v_mfma_f32_16x16x32_bf16 v[0:3], v[176:179], v[210:213], v[0:3]
	v_mfma_f32_16x16x32_bf16 v[48:51], v[172:175], v[190:193], v[48:51]
	v_mfma_f32_16x16x32_bf16 v[40:43], v[180:183], v[190:193], v[40:43]
	v_mfma_f32_16x16x32_bf16 v[32:35], v[172:175], v[198:201], v[32:35]
	v_mfma_f32_16x16x32_bf16 v[24:27], v[180:183], v[198:201], v[24:27]
	v_mfma_f32_16x16x32_bf16 v[16:19], v[172:175], v[206:209], v[16:19]
	v_mfma_f32_16x16x32_bf16 v[8:11], v[180:183], v[206:209], v[8:11]
	v_mfma_f32_16x16x32_bf16 v[4:7], v[172:175], v[214:217], v[4:7]
	v_mfma_f32_16x16x32_bf16 v[0:3], v[180:183], v[214:217], v[0:3]
	s_barrier
	s_add_i32 s33, 0, 0x18000
	s_add_i32 s60, 0, 0x1c000
	v_add_u32_e32 v164, s33, v147
	v_add_u32_e32 v180, s60, v147
	s_add_u32 s28, s40, 0x4000
	s_addc_u32 s29, s41, 0
	s_mov_b32 m0, s42
	v_lshl_add_u64 v[224:225], s[28:29], 0, v[128:129]
	global_load_lds_dwordx4 v[224:225], off
	v_lshl_add_u64 v[224:225], s[28:29], 0, v[132:133]
	s_mov_b32 m0, s43
	s_nop 0
	global_load_lds_dwordx4 v[224:225], off
	ds_read_b128 v[152:155], v164
	ds_read_b128 v[156:159], v164 offset:1024
	ds_read_b128 v[160:163], v164 offset:2048
	ds_read_b128 v[164:167], v164 offset:3072
	ds_read_b128 v[168:171], v180
	ds_read_b128 v[172:175], v180 offset:1024
	ds_read_b128 v[176:179], v180 offset:2048
	ds_read_b128 v[180:183], v180 offset:3072
	ds_read_b128 v[184:187], v151 offset:32768
	ds_read_b128 v[190:193], v151 offset:33792
	ds_read_b128 v[194:197], v151 offset:34816
	ds_read_b128 v[198:201], v151 offset:35840
	ds_read_b128 v[202:205], v151 offset:36864
	ds_read_b128 v[206:209], v151 offset:37888
	ds_read_b128 v[210:213], v151 offset:38912
	ds_read_b128 v[214:217], v151 offset:39936
	s_waitcnt vmcnt(8)
	s_waitcnt lgkmcnt(0)
	s_nop 0
	s_barrier
	s_waitcnt lgkmcnt(0)
	v_mfma_f32_16x16x32_bf16 v[124:127], v[152:155], v[184:187], v[124:127]
	v_mfma_f32_16x16x32_bf16 v[120:123], v[160:163], v[184:187], v[120:123]
	v_mfma_f32_16x16x32_bf16 v[116:119], v[152:155], v[194:197], v[116:119]
	v_mfma_f32_16x16x32_bf16 v[108:111], v[160:163], v[194:197], v[108:111]
	v_mfma_f32_16x16x32_bf16 v[100:103], v[152:155], v[202:205], v[100:103]
	v_mfma_f32_16x16x32_bf16 v[92:95], v[160:163], v[202:205], v[92:95]
	v_mfma_f32_16x16x32_bf16 v[84:87], v[152:155], v[210:213], v[84:87]
	v_mfma_f32_16x16x32_bf16 v[76:79], v[160:163], v[210:213], v[76:79]
	v_mfma_f32_16x16x32_bf16 v[124:127], v[156:159], v[190:193], v[124:127]
	v_mfma_f32_16x16x32_bf16 v[120:123], v[164:167], v[190:193], v[120:123]
	v_mfma_f32_16x16x32_bf16 v[116:119], v[156:159], v[198:201], v[116:119]
	v_mfma_f32_16x16x32_bf16 v[108:111], v[164:167], v[198:201], v[108:111]
	v_mfma_f32_16x16x32_bf16 v[100:103], v[156:159], v[206:209], v[100:103]
	v_mfma_f32_16x16x32_bf16 v[92:95], v[164:167], v[206:209], v[92:95]
	v_mfma_f32_16x16x32_bf16 v[84:87], v[156:159], v[214:217], v[84:87]
	v_mfma_f32_16x16x32_bf16 v[76:79], v[164:167], v[214:217], v[76:79]
	v_mfma_f32_16x16x32_bf16 v[112:115], v[168:171], v[184:187], v[112:115]
	v_mfma_f32_16x16x32_bf16 v[104:107], v[176:179], v[184:187], v[104:107]
	v_mfma_f32_16x16x32_bf16 v[96:99], v[168:171], v[194:197], v[96:99]
	v_mfma_f32_16x16x32_bf16 v[88:91], v[176:179], v[194:197], v[88:91]
	v_mfma_f32_16x16x32_bf16 v[80:83], v[168:171], v[202:205], v[80:83]
	v_mfma_f32_16x16x32_bf16 v[72:75], v[176:179], v[202:205], v[72:75]
	v_mfma_f32_16x16x32_bf16 v[68:71], v[168:171], v[210:213], v[68:71]
	v_mfma_f32_16x16x32_bf16 v[64:67], v[176:179], v[210:213], v[64:67]
	v_mfma_f32_16x16x32_bf16 v[112:115], v[172:175], v[190:193], v[112:115]
	v_mfma_f32_16x16x32_bf16 v[104:107], v[180:183], v[190:193], v[104:107]
	v_mfma_f32_16x16x32_bf16 v[96:99], v[172:175], v[198:201], v[96:99]
	v_mfma_f32_16x16x32_bf16 v[88:91], v[180:183], v[198:201], v[88:91]
	v_mfma_f32_16x16x32_bf16 v[80:83], v[172:175], v[206:209], v[80:83]
	v_mfma_f32_16x16x32_bf16 v[72:75], v[180:183], v[206:209], v[72:75]
	v_mfma_f32_16x16x32_bf16 v[68:71], v[172:175], v[214:217], v[68:71]
	v_mfma_f32_16x16x32_bf16 v[64:67], v[180:183], v[214:217], v[64:67]
	s_barrier
	s_add_i32 s28, s33, s13
	v_lshl_add_u64 v[144:145], v[144:145], 0, s[8:9]
	s_mov_b32 m0, s28
	s_nop 0
	global_load_lds_dwordx4 v[144:145], off
	s_add_i32 m0, s28, 0x2000
	s_add_u32 s28, s38, 0xb0080
	v_lshl_add_u64 v[144:145], v[218:219], 0, s[8:9]
	s_addc_u32 s29, s39, 0
	s_add_i32 s33, s60, s13
	global_load_lds_dwordx4 v[144:145], off
	v_lshl_add_u64 v[144:145], s[28:29], 0, v[130:131]
	s_mov_b32 m0, s33
	s_nop 0
	global_load_lds_dwordx4 v[144:145], off
	v_lshl_add_u64 v[144:145], s[28:29], 0, v[134:135]
	s_add_i32 m0, s33, 0x2000
	s_nop 0
	global_load_lds_dwordx4 v[144:145], off
	v_lshl_add_u64 v[144:145], v[220:221], 0, s[92:93]
	s_mov_b32 m0, s45
	s_nop 0
	global_load_lds_dwordx4 v[144:145], off
	v_lshl_add_u64 v[144:145], v[222:223], 0, s[92:93]
	s_mov_b32 m0, s46
	s_nop 0
	global_load_lds_dwordx4 v[144:145], off
	ds_read_b128 v[184:187], v151 offset:49152
	ds_read_b128 v[190:193], v151 offset:50176
	ds_read_b128 v[194:197], v151 offset:51200
	ds_read_b128 v[198:201], v151 offset:52224
	ds_read_b128 v[202:205], v151 offset:53248
	ds_read_b128 v[206:209], v151 offset:54272
	ds_read_b128 v[210:213], v151 offset:55296
	ds_read_b128 v[214:217], v151 offset:56320
	s_waitcnt vmcnt(8)
	s_waitcnt lgkmcnt(0)
	s_nop 0
	s_barrier
	s_waitcnt lgkmcnt(0)
	v_mfma_f32_16x16x32_bf16 v[60:63], v[152:155], v[184:187], v[60:63]
	v_mfma_f32_16x16x32_bf16 v[56:59], v[160:163], v[184:187], v[56:59]
	v_mfma_f32_16x16x32_bf16 v[52:55], v[152:155], v[194:197], v[52:55]
	v_mfma_f32_16x16x32_bf16 v[44:47], v[160:163], v[194:197], v[44:47]
	v_mfma_f32_16x16x32_bf16 v[36:39], v[152:155], v[202:205], v[36:39]
	v_mfma_f32_16x16x32_bf16 v[28:31], v[160:163], v[202:205], v[28:31]
	v_mfma_f32_16x16x32_bf16 v[20:23], v[152:155], v[210:213], v[20:23]
	v_mfma_f32_16x16x32_bf16 v[12:15], v[160:163], v[210:213], v[12:15]
	v_mfma_f32_16x16x32_bf16 v[60:63], v[156:159], v[190:193], v[60:63]
	v_mfma_f32_16x16x32_bf16 v[56:59], v[164:167], v[190:193], v[56:59]
	v_mfma_f32_16x16x32_bf16 v[52:55], v[156:159], v[198:201], v[52:55]
	v_mfma_f32_16x16x32_bf16 v[44:47], v[164:167], v[198:201], v[44:47]
	v_mfma_f32_16x16x32_bf16 v[36:39], v[156:159], v[206:209], v[36:39]
	v_mfma_f32_16x16x32_bf16 v[28:31], v[164:167], v[206:209], v[28:31]
	v_mfma_f32_16x16x32_bf16 v[20:23], v[156:159], v[214:217], v[20:23]
	v_mfma_f32_16x16x32_bf16 v[12:15], v[164:167], v[214:217], v[12:15]
	v_mfma_f32_16x16x32_bf16 v[48:51], v[168:171], v[184:187], v[48:51]
	v_mfma_f32_16x16x32_bf16 v[40:43], v[176:179], v[184:187], v[40:43]
	v_mfma_f32_16x16x32_bf16 v[32:35], v[168:171], v[194:197], v[32:35]
	v_mfma_f32_16x16x32_bf16 v[24:27], v[176:179], v[194:197], v[24:27]
	v_mfma_f32_16x16x32_bf16 v[16:19], v[168:171], v[202:205], v[16:19]
	v_mfma_f32_16x16x32_bf16 v[8:11], v[176:179], v[202:205], v[8:11]
	v_mfma_f32_16x16x32_bf16 v[4:7], v[168:171], v[210:213], v[4:7]
	v_mfma_f32_16x16x32_bf16 v[0:3], v[176:179], v[210:213], v[0:3]
	v_mfma_f32_16x16x32_bf16 v[48:51], v[172:175], v[190:193], v[48:51]
	v_mfma_f32_16x16x32_bf16 v[40:43], v[180:183], v[190:193], v[40:43]
	v_mfma_f32_16x16x32_bf16 v[32:35], v[172:175], v[198:201], v[32:35]
	v_mfma_f32_16x16x32_bf16 v[24:27], v[180:183], v[198:201], v[24:27]
	v_mfma_f32_16x16x32_bf16 v[16:19], v[172:175], v[206:209], v[16:19]
	v_mfma_f32_16x16x32_bf16 v[8:11], v[180:183], v[206:209], v[8:11]
	v_mfma_f32_16x16x32_bf16 v[4:7], v[172:175], v[214:217], v[4:7]
	v_mfma_f32_16x16x32_bf16 v[0:3], v[180:183], v[214:217], v[0:3]
	s_barrier
	s_add_i32 s59, s59, 2
	s_add_u32 s57, s57, 0x100
	s_addc_u32 s58, s58, 0
	s_cmp_gt_u32 s59, 41
	s_mov_b64 s[28:29], s[36:37]
	s_cbranch_scc0 .LBB0_1388
	s_and_b64 vcc, exec, s[10:11]
	s_cbranch_vccz .LBB0_1391
	s_barrier
